# v35 + phase_up Q epilogue RoPE blocks: all four cos/sin loads of a block issued together
# baseline (speedup 1.0000x reference)
.LBB0_972:
	s_or_b64 exec, exec, s[0:1]
	v_add_u32_e32 v154, v3, v139
	v_ashrrev_i32_e32 v155, 31, v154
	v_lshlrev_b64 v[2:3], v2, v[154:155]
	v_mov_b32_e32 v145, v4
	v_lshl_add_u64 v[146:147], s[26:27], 0, v[146:147]
	v_lshl_add_u64 v[2:3], v[2:3], 0, v[144:145]
	v_mad_u64_u32 v[144:145], s[0:1], v2, s50, v[146:147]
	v_mad_i32_i24 v145, v3, s50, v145
	v_ashrrev_i32_e32 v135, 31, v134
	v_lshl_add_u64 v[144:145], v[134:135], 1, v[144:145]
	v_lshlrev_b32_e32 v2, 1, v152
	v_mov_b32_e32 v3, v4
	v_pk_mul_f32 v[118:119], v[118:119], s[64:65] op_sel_hi:[1,0]
	v_pk_mul_f32 v[120:121], v[120:121], s[64:65] op_sel_hi:[1,0]
	v_lshl_add_u64 v[144:145], v[144:145], 0, v[2:3]
	v_cvt_pk_bf16_f32 v118, v118, v119
	v_cvt_pk_bf16_f32 v119, v120, v121
	s_nop 0
	v_readfirstlane_b32 s70, v144
	v_readfirstlane_b32 s71, v145
	ds_write_b64 v182, v[118:119]
	v_pk_mul_f32 v[118:119], v[122:123], s[64:65] op_sel_hi:[1,0]
	v_pk_mul_f32 v[120:121], v[124:125], s[64:65] op_sel_hi:[1,0]
	v_cvt_pk_bf16_f32 v118, v118, v119
	v_cvt_pk_bf16_f32 v119, v120, v121
	ds_write_b64 v182, v[118:119] offset:16
	v_pk_mul_f32 v[118:119], v[126:127], s[64:65] op_sel_hi:[1,0]
	v_pk_mul_f32 v[120:121], v[128:129], s[64:65] op_sel_hi:[1,0]
	v_cvt_pk_bf16_f32 v118, v118, v119
	v_cvt_pk_bf16_f32 v119, v120, v121
	ds_write_b64 v182, v[118:119] offset:32
	v_pk_mul_f32 v[118:119], v[130:131], s[64:65] op_sel_hi:[1,0]
	v_pk_mul_f32 v[120:121], v[132:133], s[64:65] op_sel_hi:[1,0]
	v_cvt_pk_bf16_f32 v118, v118, v119
	v_cvt_pk_bf16_f32 v119, v120, v121
	v_mov_b64_e32 v[122:123], 0xb152000
	v_mov_b64_e32 v[120:121], 8
	v_mov_b32_e32 v3, v148
	ds_write_b64 v182, v[118:119] offset:48
	ds_read_b128 v[186:189], v183
	ds_read_b128 v[190:193], v183 offset:1280
	s_and_saveexec_b64 s[0:1], s[6:7]
	v_mov_b64_e32 v[122:123], 0xbd52000
	v_mov_b64_e32 v[120:121], 12
	v_mov_b32_e32 v3, v150
	v_mov_b32_e32 v136, v137
	s_or_b64 exec, exec, s[0:1]
	v_or_b32_e32 v1, 32, v151
	s_mov_b32 s0, 0x2aaaaaab
	v_mul_hi_i32 v118, v1, s0
	v_lshrrev_b32_e32 v119, 31, v118
	v_ashrrev_i32_e32 v118, 4, v118
	v_add_u32_e32 v121, v118, v119
	s_movk_i32 s0, 0x60
	v_mul_lo_u32 v118, v121, s0
	v_sub_u32_e32 v118, v1, v118
	v_cmp_eq_u32_e64 s[4:5], 64, v118
	s_and_b64 s[6:7], s[6:7], s[4:5]
	s_and_saveexec_b64 s[0:1], s[6:7]
	s_cbranch_execz .LBB0_976
	v_readlane_b32 s6, v253, 31
	v_lshlrev_b32_e32 v124, 7, v136
	v_mov_b32_e32 v125, v4
	v_readlane_b32 s7, v253, 32
	v_mov_b32_e32 v1, v4
	s_nop 0
	v_lshl_add_u64 v[126:127], s[6:7], 0, v[124:125]
	v_readlane_b32 s6, v254, 47
	v_readlane_b32 s7, v254, 48
	v_lshl_add_u64 v[132:133], v[126:127], 0, v[0:1]
	s_nop 0
	v_lshl_add_u64 v[124:125], s[6:7], 0, v[124:125]
	v_lshl_add_u64 v[144:145], v[124:125], 0, v[0:1]
	global_load_dwordx4 v[124:127], v[132:133], off
	global_load_dwordx4 v[128:131], v[144:145], off
	global_load_dwordx4 v[194:197], v[132:133], off offset:64
	global_load_dwordx4 v[198:201], v[144:145], off offset:64
	s_waitcnt vmcnt(2)
	v_pk_mul_f32 v[146:147], v[106:107], v[128:129]
	s_nop 0
	v_pk_fma_f32 v[146:147], v[102:103], v[124:125], v[146:147] neg_lo:[0,0,1] neg_hi:[0,0,1]
	v_pk_mul_f32 v[102:103], v[102:103], v[128:129]
	s_nop 0
	v_pk_fma_f32 v[106:107], v[106:107], v[124:125], v[102:103]
	v_pk_mul_f32 v[102:103], v[108:109], v[130:131]
	s_nop 0
	v_pk_fma_f32 v[128:129], v[104:105], v[126:127], v[102:103] neg_lo:[0,0,1] neg_hi:[0,0,1]
	v_pk_mul_f32 v[102:103], v[104:105], v[130:131]
	s_nop 0
	v_pk_fma_f32 v[108:109], v[108:109], v[126:127], v[102:103]
	s_waitcnt vmcnt(0)
	v_pk_mul_f32 v[130:131], v[114:115], v[198:199]
	s_nop 0
	v_pk_fma_f32 v[130:131], v[110:111], v[194:195], v[130:131] neg_lo:[0,0,1] neg_hi:[0,0,1]
	v_pk_mul_f32 v[110:111], v[110:111], v[198:199]
	s_nop 0
	v_pk_fma_f32 v[114:115], v[114:115], v[194:195], v[110:111]
	v_pk_mul_f32 v[102:103], v[116:117], v[200:201]
	v_mov_b32_e32 v110, v130
	v_pk_fma_f32 v[124:125], v[112:113], v[196:197], v[102:103] neg_lo:[0,0,1] neg_hi:[0,0,1]
	v_pk_mul_f32 v[102:103], v[112:113], v[200:201]
	v_mov_b32_e32 v111, v131
	v_pk_fma_f32 v[116:117], v[116:117], v[196:197], v[102:103]
	v_mov_b32_e32 v102, v146
	v_mov_b32_e32 v103, v147
	v_mov_b32_e32 v104, v128
	v_mov_b32_e32 v105, v129
	v_mov_b32_e32 v112, v124
	v_mov_b32_e32 v113, v125
.LBB0_976:
	s_or_b64 exec, exec, s[0:1]
	v_add_u32_e32 v124, v3, v121
	v_ashrrev_i32_e32 v125, 31, v124
	v_lshlrev_b64 v[124:125], v120, v[124:125]
	v_mov_b32_e32 v137, v4
	v_lshl_add_u64 v[122:123], s[26:27], 0, v[122:123]
	v_lshl_add_u64 v[124:125], v[124:125], 0, v[136:137]
	v_mad_u64_u32 v[122:123], s[0:1], v124, s50, v[122:123]
	v_mad_i32_i24 v123, v125, s50, v123
	v_ashrrev_i32_e32 v119, 31, v118
	v_lshl_add_u64 v[122:123], v[118:119], 1, v[122:123]
	v_mov_b32_e32 v3, v4
	v_pk_mul_f32 v[102:103], v[102:103], s[64:65] op_sel_hi:[1,0]
	v_pk_mul_f32 v[104:105], v[104:105], s[64:65] op_sel_hi:[1,0]
	v_lshl_add_u64 v[122:123], v[122:123], 0, v[2:3]
	v_cvt_pk_bf16_f32 v102, v102, v103
	v_cvt_pk_bf16_f32 v103, v104, v105
	s_waitcnt lgkmcnt(0)
	global_store_dwordx4 v184, v[186:189], s[70:71]
	global_store_dwordx4 v184, v[190:193], s[70:71] offset:3072
	s_nop 0
	v_readfirstlane_b32 s70, v122
	v_readfirstlane_b32 s71, v123
	ds_write_b64 v182, v[102:103]
	v_pk_mul_f32 v[102:103], v[106:107], s[64:65] op_sel_hi:[1,0]
	v_pk_mul_f32 v[104:105], v[108:109], s[64:65] op_sel_hi:[1,0]
	v_cvt_pk_bf16_f32 v102, v102, v103
	v_cvt_pk_bf16_f32 v103, v104, v105
	ds_write_b64 v182, v[102:103] offset:16
	v_pk_mul_f32 v[102:103], v[110:111], s[64:65] op_sel_hi:[1,0]
	v_pk_mul_f32 v[104:105], v[112:113], s[64:65] op_sel_hi:[1,0]
	v_cvt_pk_bf16_f32 v102, v102, v103
	v_cvt_pk_bf16_f32 v103, v104, v105
	ds_write_b64 v182, v[102:103] offset:32
	v_pk_mul_f32 v[102:103], v[114:115], s[64:65] op_sel_hi:[1,0]
	v_pk_mul_f32 v[104:105], v[116:117], s[64:65] op_sel_hi:[1,0]
	v_or_b32_e32 v1, 32, v149
	v_cvt_pk_bf16_f32 v102, v102, v103
	v_cvt_pk_bf16_f32 v103, v104, v105
	v_cmp_lt_i32_e64 s[6:7], s89, v1
	s_movk_i32 s0, 0xbf
	v_add_u32_e32 v1, 0xffffe020, v149
	ds_write_b64 v182, v[102:103] offset:48
	ds_read_b128 v[186:189], v183
	ds_read_b128 v[190:193], v183 offset:1280
	v_bitop3_b32 v102, v149, s0, 32 bitop3:0xc8
	s_movk_i32 s0, 0xfbf
	v_lshrrev_b32_e32 v1, 9, v1
	v_bitop3_b32 v103, v149, s0, 32 bitop3:0xc8
	v_and_b32_e32 v110, 0x7ffff8, v1
	v_mov_b64_e32 v[108:109], 0xb152000
	v_mov_b64_e32 v[104:105], 8
	v_mov_b32_e32 v3, v148
	v_mov_b32_e32 v106, v102
	s_and_saveexec_b64 s[0:1], s[6:7]
	v_mov_b64_e32 v[108:109], 0xbd52000
	v_mov_b64_e32 v[104:105], 12
	v_mov_b32_e32 v3, v110
	v_mov_b32_e32 v106, v103
	s_or_b64 exec, exec, s[0:1]
	s_and_b64 s[14:15], s[6:7], vcc
	s_and_saveexec_b64 s[0:1], s[14:15]
	s_cbranch_execz .LBB0_980
	v_readlane_b32 s14, v253, 31
	v_lshlrev_b32_e32 v112, 7, v106
	v_mov_b32_e32 v113, v4
	v_readlane_b32 s15, v253, 32
	v_mov_b32_e32 v1, v4
	s_nop 0
	v_lshl_add_u64 v[114:115], s[14:15], 0, v[112:113]
	v_readlane_b32 s14, v254, 47
	v_readlane_b32 s15, v254, 48
	v_lshl_add_u64 v[116:117], v[114:115], 0, v[0:1]
	s_nop 0
	v_lshl_add_u64 v[112:113], s[14:15], 0, v[112:113]
	v_lshl_add_u64 v[126:127], v[112:113], 0, v[0:1]
	global_load_dwordx4 v[112:115], v[116:117], off
	global_load_dwordx4 v[122:125], v[126:127], off
	global_load_dwordx4 v[194:197], v[116:117], off offset:64
	global_load_dwordx4 v[198:201], v[126:127], off offset:64
	s_waitcnt vmcnt(2)
	v_pk_mul_f32 v[128:129], v[90:91], v[122:123]
	s_nop 0
	v_pk_fma_f32 v[128:129], v[86:87], v[112:113], v[128:129] neg_lo:[0,0,1] neg_hi:[0,0,1]
	v_pk_mul_f32 v[86:87], v[86:87], v[122:123]
	s_nop 0
	v_pk_fma_f32 v[90:91], v[90:91], v[112:113], v[86:87]
	v_pk_mul_f32 v[86:87], v[92:93], v[124:125]
	s_nop 0
	v_pk_fma_f32 v[122:123], v[88:89], v[114:115], v[86:87] neg_lo:[0,0,1] neg_hi:[0,0,1]
	v_pk_mul_f32 v[86:87], v[88:89], v[124:125]
	s_nop 0
	v_pk_fma_f32 v[92:93], v[92:93], v[114:115], v[86:87]
	s_waitcnt vmcnt(0)
	v_pk_mul_f32 v[116:117], v[98:99], v[198:199]
	s_nop 0
	v_pk_fma_f32 v[116:117], v[94:95], v[194:195], v[116:117] neg_lo:[0,0,1] neg_hi:[0,0,1]
	v_pk_mul_f32 v[94:95], v[94:95], v[198:199]
	s_nop 0
	v_pk_fma_f32 v[98:99], v[98:99], v[194:195], v[94:95]
	v_pk_mul_f32 v[86:87], v[100:101], v[200:201]
	v_mov_b32_e32 v94, v116
	v_pk_fma_f32 v[112:113], v[96:97], v[196:197], v[86:87] neg_lo:[0,0,1] neg_hi:[0,0,1]
	v_pk_mul_f32 v[86:87], v[96:97], v[200:201]
	v_mov_b32_e32 v95, v117
	v_pk_fma_f32 v[100:101], v[100:101], v[196:197], v[86:87]
	v_mov_b32_e32 v86, v128
	v_mov_b32_e32 v87, v129
	v_mov_b32_e32 v88, v122
	v_mov_b32_e32 v89, v123
	v_mov_b32_e32 v96, v112
	v_mov_b32_e32 v97, v113
.LBB0_980:
	s_or_b64 exec, exec, s[0:1]
	v_add_u32_e32 v112, v3, v139
	v_ashrrev_i32_e32 v113, 31, v112
	v_lshlrev_b64 v[104:105], v104, v[112:113]
	v_mov_b32_e32 v107, v4
	v_lshl_add_u64 v[108:109], s[26:27], 0, v[108:109]
	v_lshl_add_u64 v[104:105], v[104:105], 0, v[106:107]
	v_mad_u64_u32 v[106:107], s[0:1], v104, s50, v[108:109]
	v_mad_i32_i24 v107, v105, s50, v107
	v_lshl_add_u64 v[104:105], v[134:135], 1, v[106:107]
	v_mov_b32_e32 v3, v4
	v_pk_mul_f32 v[86:87], v[86:87], s[64:65] op_sel_hi:[1,0]
	v_pk_mul_f32 v[88:89], v[88:89], s[64:65] op_sel_hi:[1,0]
	v_lshl_add_u64 v[104:105], v[104:105], 0, v[2:3]
	v_cvt_pk_bf16_f32 v86, v86, v87
	v_cvt_pk_bf16_f32 v87, v88, v89
	s_waitcnt lgkmcnt(0)
	global_store_dwordx4 v184, v[186:189], s[70:71]
	global_store_dwordx4 v184, v[190:193], s[70:71] offset:3072
	s_nop 0
	v_readfirstlane_b32 s70, v104
	v_readfirstlane_b32 s71, v105
	ds_write_b64 v182, v[86:87]
	v_pk_mul_f32 v[86:87], v[90:91], s[64:65] op_sel_hi:[1,0]
	v_pk_mul_f32 v[88:89], v[92:93], s[64:65] op_sel_hi:[1,0]
	v_cvt_pk_bf16_f32 v86, v86, v87
	v_cvt_pk_bf16_f32 v87, v88, v89
	ds_write_b64 v182, v[86:87] offset:16
	v_pk_mul_f32 v[86:87], v[94:95], s[64:65] op_sel_hi:[1,0]
	v_pk_mul_f32 v[88:89], v[96:97], s[64:65] op_sel_hi:[1,0]
	v_cvt_pk_bf16_f32 v86, v86, v87
	v_cvt_pk_bf16_f32 v87, v88, v89
	ds_write_b64 v182, v[86:87] offset:32
	v_pk_mul_f32 v[86:87], v[98:99], s[64:65] op_sel_hi:[1,0]
	v_pk_mul_f32 v[88:89], v[100:101], s[64:65] op_sel_hi:[1,0]
	v_cvt_pk_bf16_f32 v86, v86, v87
	v_cvt_pk_bf16_f32 v87, v88, v89
	ds_write_b64 v182, v[86:87] offset:48
	ds_read_b128 v[186:189], v183
	ds_read_b128 v[190:193], v183 offset:1280
	v_mov_b64_e32 v[88:89], 0xb152000
	v_mov_b64_e32 v[86:87], 8
	v_mov_b32_e32 v3, v148
	s_and_saveexec_b64 s[0:1], s[6:7]
	v_mov_b64_e32 v[88:89], 0xbd52000
	v_mov_b64_e32 v[86:87], 12
	v_mov_b32_e32 v3, v110
	v_mov_b32_e32 v102, v103
	s_or_b64 exec, exec, s[0:1]
	s_and_b64 s[6:7], s[6:7], s[4:5]
	s_and_saveexec_b64 s[0:1], s[6:7]
	s_cbranch_execz .LBB0_984
	v_readlane_b32 s6, v253, 31
	v_lshlrev_b32_e32 v90, 7, v102
	v_mov_b32_e32 v91, v4
	v_readlane_b32 s7, v253, 32
	v_mov_b32_e32 v1, v4
	s_nop 0
	v_lshl_add_u64 v[92:93], s[6:7], 0, v[90:91]
	v_readlane_b32 s6, v254, 47
	v_readlane_b32 s7, v254, 48
	v_lshl_add_u64 v[98:99], v[92:93], 0, v[0:1]
	s_nop 0
	v_lshl_add_u64 v[90:91], s[6:7], 0, v[90:91]
	v_lshl_add_u64 v[100:101], v[90:91], 0, v[0:1]
	global_load_dwordx4 v[90:93], v[98:99], off
	global_load_dwordx4 v[94:97], v[100:101], off
	global_load_dwordx4 v[194:197], v[98:99], off offset:64
	global_load_dwordx4 v[198:201], v[100:101], off offset:64
	s_waitcnt vmcnt(2)
	v_pk_mul_f32 v[104:105], v[74:75], v[94:95]
	s_nop 0
	v_pk_fma_f32 v[104:105], v[70:71], v[90:91], v[104:105] neg_lo:[0,0,1] neg_hi:[0,0,1]
	v_pk_mul_f32 v[70:71], v[70:71], v[94:95]
	s_nop 0
	v_pk_fma_f32 v[74:75], v[74:75], v[90:91], v[70:71]
	v_pk_mul_f32 v[70:71], v[76:77], v[96:97]
	s_nop 0
	v_pk_fma_f32 v[94:95], v[72:73], v[92:93], v[70:71] neg_lo:[0,0,1] neg_hi:[0,0,1]
	v_pk_mul_f32 v[70:71], v[72:73], v[96:97]
	s_nop 0
	v_pk_fma_f32 v[76:77], v[76:77], v[92:93], v[70:71]
	s_waitcnt vmcnt(0)
	v_pk_mul_f32 v[96:97], v[82:83], v[198:199]
	s_nop 0
	v_pk_fma_f32 v[96:97], v[78:79], v[194:195], v[96:97] neg_lo:[0,0,1] neg_hi:[0,0,1]
	v_pk_mul_f32 v[78:79], v[78:79], v[198:199]
	s_nop 0
	v_pk_fma_f32 v[82:83], v[82:83], v[194:195], v[78:79]
	v_pk_mul_f32 v[70:71], v[84:85], v[200:201]
	v_mov_b32_e32 v78, v96
	v_pk_fma_f32 v[90:91], v[80:81], v[196:197], v[70:71] neg_lo:[0,0,1] neg_hi:[0,0,1]
	v_pk_mul_f32 v[70:71], v[80:81], v[200:201]
	v_mov_b32_e32 v79, v97
	v_pk_fma_f32 v[84:85], v[84:85], v[196:197], v[70:71]
	v_mov_b32_e32 v70, v104
	v_mov_b32_e32 v71, v105
	v_mov_b32_e32 v72, v94
	v_mov_b32_e32 v73, v95
	v_mov_b32_e32 v80, v90
	v_mov_b32_e32 v81, v91
.LBB0_984:
	s_or_b64 exec, exec, s[0:1]
	v_add_u32_e32 v90, v3, v121
	v_ashrrev_i32_e32 v91, 31, v90
	v_lshlrev_b64 v[86:87], v86, v[90:91]
	v_mov_b32_e32 v103, v4
	v_lshl_add_u64 v[88:89], s[26:27], 0, v[88:89]
	v_lshl_add_u64 v[86:87], v[86:87], 0, v[102:103]
	v_mad_u64_u32 v[88:89], s[0:1], v86, s50, v[88:89]
	v_mad_i32_i24 v89, v87, s50, v89
	v_lshl_add_u64 v[86:87], v[118:119], 1, v[88:89]
	v_mov_b32_e32 v3, v4
	v_pk_mul_f32 v[70:71], v[70:71], s[64:65] op_sel_hi:[1,0]
	v_pk_mul_f32 v[72:73], v[72:73], s[64:65] op_sel_hi:[1,0]
	v_lshl_add_u64 v[86:87], v[86:87], 0, v[2:3]
	v_cvt_pk_bf16_f32 v70, v70, v71
	v_cvt_pk_bf16_f32 v71, v72, v73
	s_waitcnt lgkmcnt(0)
	global_store_dwordx4 v184, v[186:189], s[70:71]
	global_store_dwordx4 v184, v[190:193], s[70:71] offset:3072
	s_nop 0
	v_readfirstlane_b32 s70, v86
	v_readfirstlane_b32 s71, v87
	ds_write_b64 v182, v[70:71]
	v_pk_mul_f32 v[70:71], v[74:75], s[64:65] op_sel_hi:[1,0]
	v_pk_mul_f32 v[72:73], v[76:77], s[64:65] op_sel_hi:[1,0]
	v_cvt_pk_bf16_f32 v70, v70, v71
	v_cvt_pk_bf16_f32 v71, v72, v73
	ds_write_b64 v182, v[70:71] offset:16
	v_pk_mul_f32 v[70:71], v[78:79], s[64:65] op_sel_hi:[1,0]
	v_pk_mul_f32 v[72:73], v[80:81], s[64:65] op_sel_hi:[1,0]
	v_cvt_pk_bf16_f32 v70, v70, v71
	v_cvt_pk_bf16_f32 v71, v72, v73
	ds_write_b64 v182, v[70:71] offset:32
	v_pk_mul_f32 v[70:71], v[82:83], s[64:65] op_sel_hi:[1,0]
	v_pk_mul_f32 v[72:73], v[84:85], s[64:65] op_sel_hi:[1,0]
	v_or_b32_e32 v1, 64, v149
	v_cvt_pk_bf16_f32 v70, v70, v71
	v_cvt_pk_bf16_f32 v71, v72, v73
	v_cmp_lt_i32_e64 s[6:7], s89, v1
	s_movk_i32 s0, 0xdf
	v_add_u32_e32 v1, 0xffffe040, v149
	ds_write_b64 v182, v[70:71] offset:48
	ds_read_b128 v[186:189], v183
	ds_read_b128 v[190:193], v183 offset:1280
	v_bitop3_b32 v70, v149, s0, 64 bitop3:0xc8
	s_movk_i32 s0, 0xfdf
	v_lshrrev_b32_e32 v1, 9, v1
	v_bitop3_b32 v71, v149, s0, 64 bitop3:0xc8
	v_and_b32_e32 v78, 0x7ffff8, v1
	v_mov_b64_e32 v[76:77], 0xb152000
	v_mov_b64_e32 v[72:73], 8
	v_mov_b32_e32 v3, v148
	v_mov_b32_e32 v74, v70
	s_and_saveexec_b64 s[0:1], s[6:7]
	v_mov_b64_e32 v[76:77], 0xbd52000
	v_mov_b64_e32 v[72:73], 12
	v_mov_b32_e32 v3, v78
	v_mov_b32_e32 v74, v71
	s_or_b64 exec, exec, s[0:1]
	s_and_b64 s[14:15], s[6:7], vcc
	s_and_saveexec_b64 s[0:1], s[14:15]
	s_cbranch_execz .LBB0_988
	v_readlane_b32 s14, v253, 31
	v_lshlrev_b32_e32 v80, 7, v74
	v_mov_b32_e32 v81, v4
	v_readlane_b32 s15, v253, 32
	v_mov_b32_e32 v1, v4
	s_nop 0
	v_lshl_add_u64 v[82:83], s[14:15], 0, v[80:81]
	v_readlane_b32 s14, v254, 47
	v_readlane_b32 s15, v254, 48
	v_lshl_add_u64 v[88:89], v[82:83], 0, v[0:1]
	s_nop 0
	v_lshl_add_u64 v[80:81], s[14:15], 0, v[80:81]
	v_lshl_add_u64 v[90:91], v[80:81], 0, v[0:1]
	global_load_dwordx4 v[80:83], v[88:89], off
	global_load_dwordx4 v[84:87], v[90:91], off
	global_load_dwordx4 v[194:197], v[88:89], off offset:64
	global_load_dwordx4 v[198:201], v[90:91], off offset:64
	s_waitcnt vmcnt(2)
	v_pk_mul_f32 v[92:93], v[58:59], v[84:85]
	s_nop 0
	v_pk_fma_f32 v[92:93], v[54:55], v[80:81], v[92:93] neg_lo:[0,0,1] neg_hi:[0,0,1]
	v_pk_mul_f32 v[54:55], v[54:55], v[84:85]
	s_nop 0
	v_pk_fma_f32 v[58:59], v[58:59], v[80:81], v[54:55]
	v_pk_mul_f32 v[54:55], v[60:61], v[86:87]
	s_nop 0
	v_pk_fma_f32 v[84:85], v[56:57], v[82:83], v[54:55] neg_lo:[0,0,1] neg_hi:[0,0,1]
	v_pk_mul_f32 v[54:55], v[56:57], v[86:87]
	s_nop 0
	v_pk_fma_f32 v[60:61], v[60:61], v[82:83], v[54:55]
	s_waitcnt vmcnt(0)
	v_pk_mul_f32 v[86:87], v[66:67], v[198:199]
	s_nop 0
	v_pk_fma_f32 v[86:87], v[62:63], v[194:195], v[86:87] neg_lo:[0,0,1] neg_hi:[0,0,1]
	v_pk_mul_f32 v[62:63], v[62:63], v[198:199]
	s_nop 0
	v_pk_fma_f32 v[66:67], v[66:67], v[194:195], v[62:63]
	v_pk_mul_f32 v[54:55], v[68:69], v[200:201]
	v_mov_b32_e32 v62, v86
	v_pk_fma_f32 v[80:81], v[64:65], v[196:197], v[54:55] neg_lo:[0,0,1] neg_hi:[0,0,1]
	v_pk_mul_f32 v[54:55], v[64:65], v[200:201]
	v_mov_b32_e32 v63, v87
	v_pk_fma_f32 v[68:69], v[68:69], v[196:197], v[54:55]
	v_mov_b32_e32 v54, v92
	v_mov_b32_e32 v55, v93
	v_mov_b32_e32 v56, v84
	v_mov_b32_e32 v57, v85
	v_mov_b32_e32 v64, v80
	v_mov_b32_e32 v65, v81
.LBB0_988:
	s_or_b64 exec, exec, s[0:1]
	v_add_u32_e32 v80, v3, v139
	v_ashrrev_i32_e32 v81, 31, v80
	v_lshlrev_b64 v[72:73], v72, v[80:81]
	v_mov_b32_e32 v75, v4
	v_lshl_add_u64 v[76:77], s[26:27], 0, v[76:77]
	v_lshl_add_u64 v[72:73], v[72:73], 0, v[74:75]
	v_mad_u64_u32 v[74:75], s[0:1], v72, s50, v[76:77]
	v_mad_i32_i24 v75, v73, s50, v75
	v_lshl_add_u64 v[72:73], v[134:135], 1, v[74:75]
	v_mov_b32_e32 v3, v4
	v_pk_mul_f32 v[54:55], v[54:55], s[64:65] op_sel_hi:[1,0]
	v_pk_mul_f32 v[56:57], v[56:57], s[64:65] op_sel_hi:[1,0]
	v_lshl_add_u64 v[72:73], v[72:73], 0, v[2:3]
	v_cvt_pk_bf16_f32 v54, v54, v55
	v_cvt_pk_bf16_f32 v55, v56, v57
	s_waitcnt lgkmcnt(0)
	global_store_dwordx4 v184, v[186:189], s[70:71]
	global_store_dwordx4 v184, v[190:193], s[70:71] offset:3072
	s_nop 0
	v_readfirstlane_b32 s70, v72
	v_readfirstlane_b32 s71, v73
	ds_write_b64 v182, v[54:55]
	v_pk_mul_f32 v[54:55], v[58:59], s[64:65] op_sel_hi:[1,0]
	v_pk_mul_f32 v[56:57], v[60:61], s[64:65] op_sel_hi:[1,0]
	v_cvt_pk_bf16_f32 v54, v54, v55
	v_cvt_pk_bf16_f32 v55, v56, v57
	ds_write_b64 v182, v[54:55] offset:16
	v_pk_mul_f32 v[54:55], v[62:63], s[64:65] op_sel_hi:[1,0]
	v_pk_mul_f32 v[56:57], v[64:65], s[64:65] op_sel_hi:[1,0]
	v_cvt_pk_bf16_f32 v54, v54, v55
	v_cvt_pk_bf16_f32 v55, v56, v57
	ds_write_b64 v182, v[54:55] offset:32
	v_pk_mul_f32 v[54:55], v[66:67], s[64:65] op_sel_hi:[1,0]
	v_pk_mul_f32 v[56:57], v[68:69], s[64:65] op_sel_hi:[1,0]
	v_cvt_pk_bf16_f32 v54, v54, v55
	v_cvt_pk_bf16_f32 v55, v56, v57
	ds_write_b64 v182, v[54:55] offset:48
	ds_read_b128 v[186:189], v183
	ds_read_b128 v[190:193], v183 offset:1280
	v_mov_b64_e32 v[56:57], 0xb152000
	v_mov_b64_e32 v[54:55], 8
	v_mov_b32_e32 v3, v148
	s_and_saveexec_b64 s[0:1], s[6:7]
	v_mov_b64_e32 v[56:57], 0xbd52000
	v_mov_b64_e32 v[54:55], 12
	v_mov_b32_e32 v3, v78
	v_mov_b32_e32 v70, v71
	s_or_b64 exec, exec, s[0:1]
	s_and_b64 s[6:7], s[6:7], s[4:5]
	s_and_saveexec_b64 s[0:1], s[6:7]
	s_cbranch_execz .LBB0_992
	v_readlane_b32 s6, v253, 31
	v_lshlrev_b32_e32 v58, 7, v70
	v_mov_b32_e32 v59, v4
	v_readlane_b32 s7, v253, 32
	v_mov_b32_e32 v1, v4
	s_nop 0
	v_lshl_add_u64 v[60:61], s[6:7], 0, v[58:59]
	v_readlane_b32 s6, v254, 47
	v_readlane_b32 s7, v254, 48
	v_lshl_add_u64 v[66:67], v[60:61], 0, v[0:1]
	s_nop 0
	v_lshl_add_u64 v[58:59], s[6:7], 0, v[58:59]
	v_lshl_add_u64 v[68:69], v[58:59], 0, v[0:1]
	global_load_dwordx4 v[58:61], v[66:67], off
	global_load_dwordx4 v[62:65], v[68:69], off
	global_load_dwordx4 v[194:197], v[66:67], off offset:64
	global_load_dwordx4 v[198:201], v[68:69], off offset:64
	s_waitcnt vmcnt(2)
	v_pk_mul_f32 v[72:73], v[42:43], v[62:63]
	s_nop 0
	v_pk_fma_f32 v[72:73], v[38:39], v[58:59], v[72:73] neg_lo:[0,0,1] neg_hi:[0,0,1]
	v_pk_mul_f32 v[38:39], v[38:39], v[62:63]
	s_nop 0
	v_pk_fma_f32 v[42:43], v[42:43], v[58:59], v[38:39]
	v_pk_mul_f32 v[38:39], v[44:45], v[64:65]
	s_nop 0
	v_pk_fma_f32 v[62:63], v[40:41], v[60:61], v[38:39] neg_lo:[0,0,1] neg_hi:[0,0,1]
	v_pk_mul_f32 v[38:39], v[40:41], v[64:65]
	s_nop 0
	v_pk_fma_f32 v[44:45], v[44:45], v[60:61], v[38:39]
	s_waitcnt vmcnt(0)
	v_pk_mul_f32 v[64:65], v[50:51], v[198:199]
	s_nop 0
	v_pk_fma_f32 v[64:65], v[46:47], v[194:195], v[64:65] neg_lo:[0,0,1] neg_hi:[0,0,1]
	v_pk_mul_f32 v[46:47], v[46:47], v[198:199]
	s_nop 0
	v_pk_fma_f32 v[50:51], v[50:51], v[194:195], v[46:47]
	v_pk_mul_f32 v[38:39], v[52:53], v[200:201]
	v_mov_b32_e32 v46, v64
	v_pk_fma_f32 v[58:59], v[48:49], v[196:197], v[38:39] neg_lo:[0,0,1] neg_hi:[0,0,1]
	v_pk_mul_f32 v[38:39], v[48:49], v[200:201]
	v_mov_b32_e32 v47, v65
	v_pk_fma_f32 v[52:53], v[52:53], v[196:197], v[38:39]
	v_mov_b32_e32 v38, v72
	v_mov_b32_e32 v39, v73
	v_mov_b32_e32 v40, v62
	v_mov_b32_e32 v41, v63
	v_mov_b32_e32 v48, v58
	v_mov_b32_e32 v49, v59
.LBB0_992:
	s_or_b64 exec, exec, s[0:1]
	v_add_u32_e32 v58, v3, v121
	v_ashrrev_i32_e32 v59, 31, v58
	v_lshlrev_b64 v[54:55], v54, v[58:59]
	v_mov_b32_e32 v71, v4
	v_lshl_add_u64 v[56:57], s[26:27], 0, v[56:57]
	v_lshl_add_u64 v[54:55], v[54:55], 0, v[70:71]
	v_mad_u64_u32 v[56:57], s[0:1], v54, s50, v[56:57]
	v_mad_i32_i24 v57, v55, s50, v57
	v_lshl_add_u64 v[54:55], v[118:119], 1, v[56:57]
	v_mov_b32_e32 v3, v4
	v_pk_mul_f32 v[38:39], v[38:39], s[64:65] op_sel_hi:[1,0]
	v_pk_mul_f32 v[40:41], v[40:41], s[64:65] op_sel_hi:[1,0]
	v_lshl_add_u64 v[54:55], v[54:55], 0, v[2:3]
	v_cvt_pk_bf16_f32 v38, v38, v39
	v_cvt_pk_bf16_f32 v39, v40, v41
	s_waitcnt lgkmcnt(0)
	global_store_dwordx4 v184, v[186:189], s[70:71]
	global_store_dwordx4 v184, v[190:193], s[70:71] offset:3072
	s_nop 0
	v_readfirstlane_b32 s70, v54
	v_readfirstlane_b32 s71, v55
	ds_write_b64 v182, v[38:39]
	v_pk_mul_f32 v[38:39], v[42:43], s[64:65] op_sel_hi:[1,0]
	v_pk_mul_f32 v[40:41], v[44:45], s[64:65] op_sel_hi:[1,0]
	v_cvt_pk_bf16_f32 v38, v38, v39
	v_cvt_pk_bf16_f32 v39, v40, v41
	ds_write_b64 v182, v[38:39] offset:16
	v_pk_mul_f32 v[38:39], v[46:47], s[64:65] op_sel_hi:[1,0]
	v_pk_mul_f32 v[40:41], v[48:49], s[64:65] op_sel_hi:[1,0]
	v_cvt_pk_bf16_f32 v38, v38, v39
	v_cvt_pk_bf16_f32 v39, v40, v41
	ds_write_b64 v182, v[38:39] offset:32
	v_pk_mul_f32 v[38:39], v[50:51], s[64:65] op_sel_hi:[1,0]
	v_pk_mul_f32 v[40:41], v[52:53], s[64:65] op_sel_hi:[1,0]
	v_or_b32_e32 v1, 0x60, v149
	v_cvt_pk_bf16_f32 v38, v38, v39
	v_cvt_pk_bf16_f32 v39, v40, v41
	v_cmp_lt_i32_e64 s[6:7], s89, v1
	s_movk_i32 s0, 0xff
	v_add_u32_e32 v1, 0xffffe060, v149
	ds_write_b64 v182, v[38:39] offset:48
	ds_read_b128 v[186:189], v183
	ds_read_b128 v[190:193], v183 offset:1280
	v_bitop3_b32 v38, v149, s0, v251 bitop3:0xc8
	s_movk_i32 s0, 0xfff
	v_lshrrev_b32_e32 v1, 9, v1
	v_bitop3_b32 v39, v149, s0, v251 bitop3:0xc8
	v_and_b32_e32 v46, 0x7ffff8, v1
	v_mov_b64_e32 v[44:45], 0xb152000
	v_mov_b64_e32 v[40:41], 8
	v_mov_b32_e32 v3, v148
	v_mov_b32_e32 v42, v38
	s_and_saveexec_b64 s[0:1], s[6:7]
	v_mov_b64_e32 v[44:45], 0xbd52000
	v_mov_b64_e32 v[40:41], 12
	v_mov_b32_e32 v3, v46
	v_mov_b32_e32 v42, v39
	s_or_b64 exec, exec, s[0:1]
	s_and_b64 s[14:15], s[6:7], vcc
	s_and_saveexec_b64 s[0:1], s[14:15]
	s_cbranch_execz .LBB0_996
	v_readlane_b32 s14, v253, 31
	v_lshlrev_b32_e32 v48, 7, v42
	v_mov_b32_e32 v49, v4
	v_readlane_b32 s15, v253, 32
	v_mov_b32_e32 v1, v4
	s_nop 0
	v_lshl_add_u64 v[50:51], s[14:15], 0, v[48:49]
	v_readlane_b32 s14, v254, 47
	v_readlane_b32 s15, v254, 48
	v_lshl_add_u64 v[56:57], v[50:51], 0, v[0:1]
	s_nop 0
	v_lshl_add_u64 v[48:49], s[14:15], 0, v[48:49]
	v_lshl_add_u64 v[58:59], v[48:49], 0, v[0:1]
	global_load_dwordx4 v[48:51], v[56:57], off
	global_load_dwordx4 v[52:55], v[58:59], off
	global_load_dwordx4 v[194:197], v[56:57], off offset:64
	global_load_dwordx4 v[198:201], v[58:59], off offset:64
	s_waitcnt vmcnt(2)
	v_pk_mul_f32 v[60:61], v[26:27], v[52:53]
	s_nop 0
	v_pk_fma_f32 v[60:61], v[22:23], v[48:49], v[60:61] neg_lo:[0,0,1] neg_hi:[0,0,1]
	v_pk_mul_f32 v[22:23], v[22:23], v[52:53]
	s_nop 0
	v_pk_fma_f32 v[26:27], v[26:27], v[48:49], v[22:23]
	v_pk_mul_f32 v[22:23], v[28:29], v[54:55]
	s_nop 0
	v_pk_fma_f32 v[52:53], v[24:25], v[50:51], v[22:23] neg_lo:[0,0,1] neg_hi:[0,0,1]
	v_pk_mul_f32 v[22:23], v[24:25], v[54:55]
	s_nop 0
	v_pk_fma_f32 v[28:29], v[28:29], v[50:51], v[22:23]
	s_waitcnt vmcnt(0)
	v_pk_mul_f32 v[54:55], v[34:35], v[198:199]
	s_nop 0
	v_pk_fma_f32 v[54:55], v[30:31], v[194:195], v[54:55] neg_lo:[0,0,1] neg_hi:[0,0,1]
	v_pk_mul_f32 v[30:31], v[30:31], v[198:199]
	s_nop 0
	v_pk_fma_f32 v[34:35], v[34:35], v[194:195], v[30:31]
	v_pk_mul_f32 v[22:23], v[36:37], v[200:201]
	v_mov_b32_e32 v30, v54
	v_pk_fma_f32 v[48:49], v[32:33], v[196:197], v[22:23] neg_lo:[0,0,1] neg_hi:[0,0,1]
	v_pk_mul_f32 v[22:23], v[32:33], v[200:201]
	v_mov_b32_e32 v31, v55
	v_pk_fma_f32 v[36:37], v[36:37], v[196:197], v[22:23]
	v_mov_b32_e32 v22, v60
	v_mov_b32_e32 v23, v61
	v_mov_b32_e32 v24, v52
	v_mov_b32_e32 v25, v53
	v_mov_b32_e32 v32, v48
	v_mov_b32_e32 v33, v49
.LBB0_996:
	s_or_b64 exec, exec, s[0:1]
	v_add_u32_e32 v48, v3, v139
	v_ashrrev_i32_e32 v49, 31, v48
	v_lshlrev_b64 v[40:41], v40, v[48:49]
	v_mov_b32_e32 v43, v4
	v_lshl_add_u64 v[44:45], s[26:27], 0, v[44:45]
	v_lshl_add_u64 v[40:41], v[40:41], 0, v[42:43]
	v_mad_u64_u32 v[42:43], s[0:1], v40, s50, v[44:45]
	v_mad_i32_i24 v43, v41, s50, v43
	v_lshl_add_u64 v[40:41], v[134:135], 1, v[42:43]
	v_mov_b32_e32 v3, v4
	v_pk_mul_f32 v[22:23], v[22:23], s[64:65] op_sel_hi:[1,0]
	v_pk_mul_f32 v[24:25], v[24:25], s[64:65] op_sel_hi:[1,0]
	v_lshl_add_u64 v[40:41], v[40:41], 0, v[2:3]
	v_cvt_pk_bf16_f32 v22, v22, v23
	v_cvt_pk_bf16_f32 v23, v24, v25
	s_waitcnt lgkmcnt(0)
	global_store_dwordx4 v184, v[186:189], s[70:71]
	global_store_dwordx4 v184, v[190:193], s[70:71] offset:3072
	s_nop 0
	v_readfirstlane_b32 s70, v40
	v_readfirstlane_b32 s71, v41
	ds_write_b64 v182, v[22:23]
	v_pk_mul_f32 v[22:23], v[26:27], s[64:65] op_sel_hi:[1,0]
	v_pk_mul_f32 v[24:25], v[28:29], s[64:65] op_sel_hi:[1,0]
	v_cvt_pk_bf16_f32 v22, v22, v23
	v_cvt_pk_bf16_f32 v23, v24, v25
	ds_write_b64 v182, v[22:23] offset:16
	v_pk_mul_f32 v[22:23], v[30:31], s[64:65] op_sel_hi:[1,0]
	v_pk_mul_f32 v[24:25], v[32:33], s[64:65] op_sel_hi:[1,0]
	v_cvt_pk_bf16_f32 v22, v22, v23
	v_cvt_pk_bf16_f32 v23, v24, v25
	ds_write_b64 v182, v[22:23] offset:32
	v_pk_mul_f32 v[22:23], v[34:35], s[64:65] op_sel_hi:[1,0]
	v_pk_mul_f32 v[24:25], v[36:37], s[64:65] op_sel_hi:[1,0]
	v_cvt_pk_bf16_f32 v22, v22, v23
	v_cvt_pk_bf16_f32 v23, v24, v25
	ds_write_b64 v182, v[22:23] offset:48
	ds_read_b128 v[186:189], v183
	ds_read_b128 v[190:193], v183 offset:1280
	v_mov_b64_e32 v[24:25], 0xb152000
	v_mov_b64_e32 v[22:23], 8
	s_and_saveexec_b64 s[0:1], s[6:7]
	v_mov_b64_e32 v[24:25], 0xbd52000
	v_mov_b64_e32 v[22:23], 12
	v_mov_b32_e32 v148, v46
	v_mov_b32_e32 v38, v39
	s_or_b64 exec, exec, s[0:1]
	s_and_b64 s[4:5], s[6:7], s[4:5]
	s_and_saveexec_b64 s[0:1], s[4:5]
	s_cbranch_execz .LBB0_915
	v_readlane_b32 s4, v253, 31
	v_lshlrev_b32_e32 v26, 7, v38
	v_mov_b32_e32 v27, v4
	v_readlane_b32 s5, v253, 32
	v_mov_b32_e32 v1, v4
	s_nop 0
	v_lshl_add_u64 v[28:29], s[4:5], 0, v[26:27]
	v_readlane_b32 s4, v254, 47
	v_readlane_b32 s5, v254, 48
	v_lshl_add_u64 v[34:35], v[28:29], 0, v[0:1]
	s_nop 0
	v_lshl_add_u64 v[26:27], s[4:5], 0, v[26:27]
	v_lshl_add_u64 v[0:1], v[26:27], 0, v[0:1]
	global_load_dwordx4 v[26:29], v[34:35], off
	global_load_dwordx4 v[30:33], v[0:1], off
	global_load_dwordx4 v[194:197], v[34:35], off offset:64
	global_load_dwordx4 v[198:201], v[0:1], off offset:64
	s_waitcnt vmcnt(2)
	v_pk_mul_f32 v[36:37], v[10:11], v[30:31]
	s_nop 0
	v_pk_fma_f32 v[36:37], v[6:7], v[26:27], v[36:37] neg_lo:[0,0,1] neg_hi:[0,0,1]
	v_pk_mul_f32 v[6:7], v[6:7], v[30:31]
	s_nop 0
	v_pk_fma_f32 v[10:11], v[10:11], v[26:27], v[6:7]
	v_pk_mul_f32 v[6:7], v[12:13], v[32:33]
	s_nop 0
	v_pk_fma_f32 v[30:31], v[8:9], v[28:29], v[6:7] neg_lo:[0,0,1] neg_hi:[0,0,1]
	v_pk_mul_f32 v[6:7], v[8:9], v[32:33]
	s_nop 0
	v_pk_fma_f32 v[12:13], v[12:13], v[28:29], v[6:7]
	s_waitcnt vmcnt(0)
	v_pk_mul_f32 v[0:1], v[18:19], v[198:199]
	s_nop 0
	v_pk_fma_f32 v[0:1], v[14:15], v[194:195], v[0:1] neg_lo:[0,0,1] neg_hi:[0,0,1]
	v_pk_mul_f32 v[14:15], v[14:15], v[198:199]
	s_nop 0
	v_pk_fma_f32 v[18:19], v[18:19], v[194:195], v[14:15]
	v_pk_mul_f32 v[6:7], v[20:21], v[200:201]
	v_mov_b32_e32 v14, v0
	v_pk_fma_f32 v[26:27], v[16:17], v[196:197], v[6:7] neg_lo:[0,0,1] neg_hi:[0,0,1]
	v_pk_mul_f32 v[6:7], v[16:17], v[200:201]
	v_mov_b32_e32 v15, v1
	v_pk_fma_f32 v[20:21], v[20:21], v[196:197], v[6:7]
	v_mov_b32_e32 v6, v36
	v_mov_b32_e32 v7, v37
	v_mov_b32_e32 v8, v30
	v_mov_b32_e32 v9, v31
	v_mov_b32_e32 v16, v26
	v_mov_b32_e32 v17, v27
	s_branch .LBB0_915
